# prologue de-serialisation in P6: all first-row parameters fetched in one batch (one wait instead of four) with row 0 already in flight
# baseline (speedup 1.0000x reference)
; __device__ __forceinline__ float bf_lo(unsigned w) { return __uint_as_float(w << 16); }
; __device__ __forceinline__ float bf_hi(unsigned w) { return __uint_as_float(w & 0xffff0000u); }
; #define FRESH() int gtid; do { int t_ = threadIdx.x; asm volatile("" : "+v"(t_)); F.tid = t_; F.lane = t_ & 63; gtid = blockIdx.x * (NWAVES * 64) + t_; (void)gtid; } while (0)
; __global__ void __launch_bounds__(NWAVES * 64, 2) mk_fwd(Args args) {
;     ...
;     if (IN(6)) { FRESH();
;         for (int row0 = F.gw * 3; row0 < MT; row0 += F.NGW * 3) {
;             f32x4 v[3][8]; u32x2 yw[3][8];
; #pragma unroll
;             for (int q = 0; q < 3; ++q) { const int row = row0 + q; const float* src = row < ML ? x + (size_t)row * DM : ctx + (size_t)(row - ML) * DM; load_row_f32(src, F.lane, v[q]);
;                 const bf16_t* yr = Y + (size_t)row * DM;
; #pragma unroll
;                 for (int j = 0; j < 8; ++j) yw[q][j] = *(const u32x2*)(yr + 4 * F.lane + 256 * j); }
; #pragma unroll
;             for (int q = 0; q < 3; ++q) { const int row = row0 + q; const bool lat = row < ML; const int r = lat ? row / SEQ : 8;
;                 float sy = 0.f;
; #pragma unroll
;                 for (int j = 0; j < 8; ++j) { const float a = bf_lo(yw[q][j].x), b = bf_hi(yw[q][j].x), c2 = bf_lo(yw[q][j].y), d = bf_hi(yw[q][j].y); sy += (a * a + b * b) + (c2 * c2 + d * d); }
;                 const float rsy = __builtin_amdgcn_rsqf(wave_sum(sy) * (1.f / DM) + EPS);
;                 const float* m0 = mod + (size_t)r * 6144;
; #pragma unroll
;                 for (int j = 0; j < 8; ++j) { const int col = 4 * F.lane + 256 * j; const f32x4 gt = *(const f32x4*)(m0 + 2 * DM + col), pn = *(const f32x4*)(post_norm + col);
.LBB0_716:
	s_cmp_lt_i32 s86, 7
	s_cselect_b64 s[4:5], -1, 0
	s_and_b64 s[0:1], s[4:5], s[0:1]
	s_andn2_b64 vcc, exec, s[0:1]
	s_cbranch_vccnz .LBB0_778
	s_cmpk_lg_i32 s63, 0x100
	s_cbranch_scc1 .Lp6_generic
	v_and_b32_e32 v194, 63, v198
	v_lshlrev_b32_e32 v192, 4, v194
	v_add_u32_e32 v193, 0x1000, v192
	v_lshlrev_b32_e32 v194, 3, v194
	v_mov_b32_e32 v195, 0x358637bd
	s_mul_i32 s6, s33, 9
	s_mov_b32 s7, -1
	s_add_i32 s0, s6, 0
	s_cmp_lt_u32 s0, 0x4000
	s_cselect_b32 s10, s68, s72
	s_cselect_b32 s11, s69, s73
	s_cselect_b32 s1, 0, 0x4000
	s_sub_i32 s1, s0, s1
	s_lshl_b32 s1, s1, 13
	s_add_u32 s10, s10, s1
	s_addc_u32 s11, s11, 0
	s_add_i32 s0, s6, 0
	s_lshl_b32 s1, s0, 12
	s_add_u32 s22, s84, s1
	s_addc_u32 s23, s85, 0
	s_add_u32 s22, s22, 0x11800000
	s_addc_u32 s23, s23, 0
	global_load_dwordx4 v[0:3], v192, s[10:11] offset:0 nt
	global_load_dwordx4 v[4:7], v192, s[10:11] offset:1024 nt
	global_load_dwordx4 v[8:11], v192, s[10:11] offset:2048 nt
	global_load_dwordx4 v[12:15], v192, s[10:11] offset:3072 nt
	global_load_dwordx4 v[16:19], v193, s[10:11] offset:0 nt
	global_load_dwordx4 v[20:23], v193, s[10:11] offset:1024 nt
	global_load_dwordx4 v[24:27], v193, s[10:11] offset:2048 nt
	global_load_dwordx4 v[28:31], v193, s[10:11] offset:3072 nt
	global_load_dwordx2 v[32:33], v194, s[22:23] offset:0
	global_load_dwordx2 v[34:35], v194, s[22:23] offset:512
	global_load_dwordx2 v[36:37], v194, s[22:23] offset:1024
	global_load_dwordx2 v[38:39], v194, s[22:23] offset:1536
	global_load_dwordx2 v[40:41], v194, s[22:23] offset:2048
	global_load_dwordx2 v[42:43], v194, s[22:23] offset:2560
	global_load_dwordx2 v[44:45], v194, s[22:23] offset:3072
	global_load_dwordx2 v[46:47], v194, s[22:23] offset:3584
	s_add_i32 s0, s6, 0
	s_add_i32 s0, s6, 0
	s_lshr_b32 s8, s0, 11
	s_cmp_lt_u32 s0, 0x4000
	s_cselect_b32 s8, s8, 8
	s_cmp_eq_u32 s8, s7
	s_cbranch_scc1 .Lp6_np0
	s_mov_b32 s7, s8
	s_add_i32 s1, s8, 9
	s_mul_i32 s1, s1, 0x6000
	s_add_u32 s44, s84, s1
	s_addc_u32 s45, s85, 0
	s_add_u32 s44, s44, 0x2000
	s_addc_u32 s45, s45, 0
	s_add_i32 s1, s8, 9
	s_mul_i32 s1, s1, 0x6000
	s_add_u32 s36, s84, s1
	s_addc_u32 s37, s85, 0
	s_add_u32 s38, s80, 0x2000
	s_addc_u32 s39, s81, 0
	s_mul_i32 s1, s8, 0x6000
	s_add_u32 s34, s84, s1
	s_addc_u32 s35, s85, 0
	s_add_u32 s34, s34, 0x4000
	s_addc_u32 s35, s35, 0
	global_load_dwordx4 v[96:99], v192, s[34:35] offset:0
	global_load_dwordx4 v[48:51], v192, s[82:83] offset:0
	global_load_dwordx4 v[128:131], v192, s[38:39] offset:0
	global_load_dwordx4 v[80:83], v192, s[44:45] offset:0
	global_load_dwordx4 v[160:163], v192, s[36:37] offset:0
	global_load_dwordx4 v[100:103], v192, s[34:35] offset:1024
	global_load_dwordx4 v[52:55], v192, s[82:83] offset:1024
	global_load_dwordx4 v[132:135], v192, s[38:39] offset:1024
	global_load_dwordx4 v[84:87], v192, s[44:45] offset:1024
	global_load_dwordx4 v[164:167], v192, s[36:37] offset:1024
	global_load_dwordx4 v[104:107], v192, s[34:35] offset:2048
	global_load_dwordx4 v[56:59], v192, s[82:83] offset:2048
	global_load_dwordx4 v[136:139], v192, s[38:39] offset:2048
	global_load_dwordx4 v[88:91], v192, s[44:45] offset:2048
	global_load_dwordx4 v[168:171], v192, s[36:37] offset:2048
	global_load_dwordx4 v[108:111], v192, s[34:35] offset:3072
	global_load_dwordx4 v[60:63], v192, s[82:83] offset:3072
	global_load_dwordx4 v[140:143], v192, s[38:39] offset:3072
	global_load_dwordx4 v[92:95], v192, s[44:45] offset:3072
	global_load_dwordx4 v[172:175], v192, s[36:37] offset:3072
	global_load_dwordx4 v[112:115], v193, s[34:35] offset:0
	global_load_dwordx4 v[64:67], v193, s[82:83] offset:0
	global_load_dwordx4 v[144:147], v193, s[38:39] offset:0
	global_load_dwordx4 v[200:203], v193, s[44:45] offset:0
	global_load_dwordx4 v[176:179], v193, s[36:37] offset:0
	global_load_dwordx4 v[116:119], v193, s[34:35] offset:1024
	global_load_dwordx4 v[68:71], v193, s[82:83] offset:1024
	global_load_dwordx4 v[148:151], v193, s[38:39] offset:1024
	global_load_dwordx4 v[204:207], v193, s[44:45] offset:1024
	global_load_dwordx4 v[180:183], v193, s[36:37] offset:1024
	global_load_dwordx4 v[120:123], v193, s[34:35] offset:2048
	global_load_dwordx4 v[72:75], v193, s[82:83] offset:2048
	global_load_dwordx4 v[152:155], v193, s[38:39] offset:2048
	global_load_dwordx4 v[208:211], v193, s[44:45] offset:2048
	global_load_dwordx4 v[184:187], v193, s[36:37] offset:2048
	global_load_dwordx4 v[124:127], v193, s[34:35] offset:3072
	global_load_dwordx4 v[76:79], v193, s[82:83] offset:3072
	global_load_dwordx4 v[156:159], v193, s[38:39] offset:3072
	global_load_dwordx4 v[212:215], v193, s[44:45] offset:3072
	global_load_dwordx4 v[188:191], v193, s[36:37] offset:3072
	s_waitcnt vmcnt(0)
; __device__ __forceinline__ unsigned cvt_pk_bf16(float lo, float hi) { unsigned r; asm volatile("v_cvt_pk_bf16_f32 %0, %1, %2" : "=v"(r) : "v"(lo), "v"(hi)); return r; }
; __device__ __forceinline__ float bf_lo(unsigned w) { return __uint_as_float(w << 16); }
; __device__ __forceinline__ float bf_hi(unsigned w) { return __uint_as_float(w & 0xffff0000u); }
; __device__ __forceinline__ void modulate_store(const f32x4 (&v)[8], float rstd, const float* pn, const float* modr, bf16_t* orow, int lane) {
; #pragma unroll
;     for (int j = 0; j < 8; ++j) { const int col = 4 * lane + 256 * j;
;         const f32x4 g = *(const f32x4*)(pn + col), sh = *(const f32x4*)(modr + col), sc = *(const f32x4*)(modr + DM + col);
;         const f32x4 hh = v[j] * rstd * g * (sc + 1.f) + sh;
;         u32x2 w; w.x = cvt_pk_bf16(hh[0], hh[1]); w.y = cvt_pk_bf16(hh[2], hh[3]);
; __global__ void __launch_bounds__(NWAVES * 64, 2) mk_fwd(Args args) {
;     ...
;         for (int row0 = F.gw * 3; row0 < MT; row0 += F.NGW * 3) {
;             f32x4 v[3][8]; u32x2 yw[3][8];
; #pragma unroll
;             for (int q = 0; q < 3; ++q) { const int row = row0 + q; const float* src = row < ML ? x + (size_t)row * DM : ctx + (size_t)(row - ML) * DM; load_row_f32(src, F.lane, v[q]);
;                 const bf16_t* yr = Y + (size_t)row * DM;
; #pragma unroll
;                 for (int j = 0; j < 8; ++j) yw[q][j] = *(const u32x2*)(yr + 4 * F.lane + 256 * j); }
;     ...
;                 const float* m0 = mod + (size_t)r * 6144;
; #pragma unroll
;                 for (int j = 0; j < 8; ++j) { const int col = 4 * F.lane + 256 * j; const f32x4 gt = *(const f32x4*)(m0 + 2 * DM + col), pn = *(const f32x4*)(post_norm + col);
;                     const f32x4 y4 = (f32x4){bf_lo(yw[q][j].x), bf_hi(yw[q][j].x), bf_lo(yw[q][j].y), bf_hi(yw[q][j].y)};
;                     v[q][j] = v[q][j] + gt * (y4 * rsy * pn);
	v_mul_f32_e32 v96, v96, v48
	v_mul_f32_e32 v97, v97, v49
	v_mul_f32_e32 v98, v98, v50
	v_mul_f32_e32 v99, v99, v51
	v_mul_f32_e32 v100, v100, v52
	v_mul_f32_e32 v101, v101, v53
	v_mul_f32_e32 v102, v102, v54
	v_mul_f32_e32 v103, v103, v55
	v_mul_f32_e32 v104, v104, v56
	v_mul_f32_e32 v105, v105, v57
	v_mul_f32_e32 v106, v106, v58
	v_mul_f32_e32 v107, v107, v59
	v_mul_f32_e32 v108, v108, v60
	v_mul_f32_e32 v109, v109, v61
	v_mul_f32_e32 v110, v110, v62
	v_mul_f32_e32 v111, v111, v63
	v_mul_f32_e32 v112, v112, v64
	v_mul_f32_e32 v113, v113, v65
	v_mul_f32_e32 v114, v114, v66
	v_mul_f32_e32 v115, v115, v67
	v_mul_f32_e32 v116, v116, v68
	v_mul_f32_e32 v117, v117, v69
	v_mul_f32_e32 v118, v118, v70
	v_mul_f32_e32 v119, v119, v71
	v_mul_f32_e32 v120, v120, v72
	v_mul_f32_e32 v121, v121, v73
	v_mul_f32_e32 v122, v122, v74
	v_mul_f32_e32 v123, v123, v75
	v_mul_f32_e32 v124, v124, v76
	v_mul_f32_e32 v125, v125, v77
	v_mul_f32_e32 v126, v126, v78
	v_mul_f32_e32 v127, v127, v79
	v_add_f32_e32 v80, 1.0, v80
	v_add_f32_e32 v81, 1.0, v81
	v_add_f32_e32 v82, 1.0, v82
	v_add_f32_e32 v83, 1.0, v83
	v_add_f32_e32 v84, 1.0, v84
	v_add_f32_e32 v85, 1.0, v85
	v_add_f32_e32 v86, 1.0, v86
	v_add_f32_e32 v87, 1.0, v87
	v_add_f32_e32 v88, 1.0, v88
	v_add_f32_e32 v89, 1.0, v89
	v_add_f32_e32 v90, 1.0, v90
	v_add_f32_e32 v91, 1.0, v91
	v_add_f32_e32 v92, 1.0, v92
	v_add_f32_e32 v93, 1.0, v93
	v_add_f32_e32 v94, 1.0, v94
	v_add_f32_e32 v95, 1.0, v95
	v_add_f32_e32 v200, 1.0, v200
	v_add_f32_e32 v201, 1.0, v201
	v_add_f32_e32 v202, 1.0, v202
	v_add_f32_e32 v203, 1.0, v203
	v_add_f32_e32 v204, 1.0, v204
	v_add_f32_e32 v205, 1.0, v205
	v_add_f32_e32 v206, 1.0, v206
	v_add_f32_e32 v207, 1.0, v207
	v_add_f32_e32 v208, 1.0, v208
	v_add_f32_e32 v209, 1.0, v209
	v_add_f32_e32 v210, 1.0, v210
	v_add_f32_e32 v211, 1.0, v211
	v_add_f32_e32 v212, 1.0, v212
	v_add_f32_e32 v213, 1.0, v213
	v_add_f32_e32 v214, 1.0, v214
	v_add_f32_e32 v215, 1.0, v215
	v_mul_f32_e32 v128, v128, v80
	v_mul_f32_e32 v129, v129, v81
	v_mul_f32_e32 v130, v130, v82
	v_mul_f32_e32 v131, v131, v83
	v_mul_f32_e32 v132, v132, v84
	v_mul_f32_e32 v133, v133, v85
	v_mul_f32_e32 v134, v134, v86
	v_mul_f32_e32 v135, v135, v87
	v_mul_f32_e32 v136, v136, v88
	v_mul_f32_e32 v137, v137, v89
	v_mul_f32_e32 v138, v138, v90
	v_mul_f32_e32 v139, v139, v91
	v_mul_f32_e32 v140, v140, v92
	v_mul_f32_e32 v141, v141, v93
	v_mul_f32_e32 v142, v142, v94
	v_mul_f32_e32 v143, v143, v95
	v_mul_f32_e32 v144, v144, v200
	v_mul_f32_e32 v145, v145, v201
	v_mul_f32_e32 v146, v146, v202
	v_mul_f32_e32 v147, v147, v203
	v_mul_f32_e32 v148, v148, v204
	v_mul_f32_e32 v149, v149, v205
	v_mul_f32_e32 v150, v150, v206
	v_mul_f32_e32 v151, v151, v207
	v_mul_f32_e32 v152, v152, v208
	v_mul_f32_e32 v153, v153, v209
	v_mul_f32_e32 v154, v154, v210
	v_mul_f32_e32 v155, v155, v211
	v_mul_f32_e32 v156, v156, v212
	v_mul_f32_e32 v157, v157, v213
	v_mul_f32_e32 v158, v158, v214
	v_mul_f32_e32 v159, v159, v215
.Lp6_np0:
	s_add_i32 s0, s6, 1
	s_cmp_lt_u32 s0, 0x4000
	s_cselect_b32 s10, s68, s72
	s_cselect_b32 s11, s69, s73
	s_cselect_b32 s1, 0, 0x4000
	s_sub_i32 s1, s0, s1
	s_lshl_b32 s1, s1, 13
	s_add_u32 s10, s10, s1
	s_addc_u32 s11, s11, 0
	s_add_i32 s0, s6, 1
	s_lshl_b32 s1, s0, 12
	s_add_u32 s22, s84, s1
	s_addc_u32 s23, s85, 0
	s_add_u32 s22, s22, 0x11800000
	s_addc_u32 s23, s23, 0
	global_load_dwordx4 v[48:51], v192, s[10:11] offset:0 nt
	global_load_dwordx4 v[52:55], v192, s[10:11] offset:1024 nt
	global_load_dwordx4 v[56:59], v192, s[10:11] offset:2048 nt
	global_load_dwordx4 v[60:63], v192, s[10:11] offset:3072 nt
	global_load_dwordx4 v[64:67], v193, s[10:11] offset:0 nt
	global_load_dwordx4 v[68:71], v193, s[10:11] offset:1024 nt
	global_load_dwordx4 v[72:75], v193, s[10:11] offset:2048 nt
	global_load_dwordx4 v[76:79], v193, s[10:11] offset:3072 nt
	global_load_dwordx2 v[80:81], v194, s[22:23] offset:0
	global_load_dwordx2 v[82:83], v194, s[22:23] offset:512
	global_load_dwordx2 v[84:85], v194, s[22:23] offset:1024
	global_load_dwordx2 v[86:87], v194, s[22:23] offset:1536
	global_load_dwordx2 v[88:89], v194, s[22:23] offset:2048
	global_load_dwordx2 v[90:91], v194, s[22:23] offset:2560
	global_load_dwordx2 v[92:93], v194, s[22:23] offset:3072
	global_load_dwordx2 v[94:95], v194, s[22:23] offset:3584
	s_waitcnt vmcnt(16)
; __device__ __forceinline__ float bf_lo(unsigned w) { return __uint_as_float(w << 16); }
; __device__ __forceinline__ float bf_hi(unsigned w) { return __uint_as_float(w & 0xffff0000u); }
; __global__ void __launch_bounds__(NWAVES * 64, 2) mk_fwd(Args args) {
;     ...
;             for (int q = 0; q < 3; ++q) { const int row = row0 + q; const bool lat = row < ML; const int r = lat ? row / SEQ : 8;
;                 float sy = 0.f;
; #pragma unroll
;                 for (int j = 0; j < 8; ++j) { const float a = bf_lo(yw[q][j].x), b = bf_hi(yw[q][j].x), c2 = bf_lo(yw[q][j].y), d = bf_hi(yw[q][j].y); sy += (a * a + b * b) + (c2 * c2 + d * d); }
;                 const float rsy = __builtin_amdgcn_rsqf(wave_sum(sy) * (1.f / DM) + EPS);
;                 const float* m0 = mod + (size_t)r * 6144;
; #pragma unroll
;                 for (int j = 0; j < 8; ++j) { const int col = 4 * F.lane + 256 * j; const f32x4 gt = *(const f32x4*)(m0 + 2 * DM + col), pn = *(const f32x4*)(post_norm + col);
;                     const f32x4 y4 = (f32x4){bf_lo(yw[q][j].x), bf_hi(yw[q][j].x), bf_lo(yw[q][j].y), bf_hi(yw[q][j].y)};
;                     v[q][j] = v[q][j] + gt * (y4 * rsy * pn);
;                     if (lat) *(f32x4*)(args.out + (size_t)row * DM + col) = v[q][j]; }
	v_lshlrev_b32_e32 v216, 16, v32
	v_and_b32_e32 v217, 0xffff0000, v32
	v_lshlrev_b32_e32 v218, 16, v33
	v_and_b32_e32 v219, 0xffff0000, v33
	v_mul_f32_e32 v222, v216, v216
	v_mul_f32_e32 v223, v217, v217
	v_fmac_f32_e32 v222, v218, v218
	v_fmac_f32_e32 v223, v219, v219
	v_lshlrev_b32_e32 v216, 16, v34
	v_and_b32_e32 v217, 0xffff0000, v34
	v_lshlrev_b32_e32 v218, 16, v35
	v_and_b32_e32 v219, 0xffff0000, v35
	v_fmac_f32_e32 v222, v216, v216
	v_fmac_f32_e32 v223, v217, v217
	v_fmac_f32_e32 v222, v218, v218
	v_fmac_f32_e32 v223, v219, v219
	v_lshlrev_b32_e32 v216, 16, v36
	v_and_b32_e32 v217, 0xffff0000, v36
	v_lshlrev_b32_e32 v218, 16, v37
	v_and_b32_e32 v219, 0xffff0000, v37
	v_fmac_f32_e32 v222, v216, v216
	v_fmac_f32_e32 v223, v217, v217
	v_fmac_f32_e32 v222, v218, v218
	v_fmac_f32_e32 v223, v219, v219
	v_lshlrev_b32_e32 v216, 16, v38
	v_and_b32_e32 v217, 0xffff0000, v38
	v_lshlrev_b32_e32 v218, 16, v39
	v_and_b32_e32 v219, 0xffff0000, v39
	v_fmac_f32_e32 v222, v216, v216
	v_fmac_f32_e32 v223, v217, v217
	v_fmac_f32_e32 v222, v218, v218
	v_fmac_f32_e32 v223, v219, v219
	v_lshlrev_b32_e32 v216, 16, v40
	v_and_b32_e32 v217, 0xffff0000, v40
	v_lshlrev_b32_e32 v218, 16, v41
	v_and_b32_e32 v219, 0xffff0000, v41
	v_fmac_f32_e32 v222, v216, v216
	v_fmac_f32_e32 v223, v217, v217
	v_fmac_f32_e32 v222, v218, v218
	v_fmac_f32_e32 v223, v219, v219
	v_lshlrev_b32_e32 v216, 16, v42
	v_and_b32_e32 v217, 0xffff0000, v42
	v_lshlrev_b32_e32 v218, 16, v43
	v_and_b32_e32 v219, 0xffff0000, v43
	v_fmac_f32_e32 v222, v216, v216
	v_fmac_f32_e32 v223, v217, v217
	v_fmac_f32_e32 v222, v218, v218
	v_fmac_f32_e32 v223, v219, v219
	v_lshlrev_b32_e32 v216, 16, v44
	v_and_b32_e32 v217, 0xffff0000, v44
	v_lshlrev_b32_e32 v218, 16, v45
	v_and_b32_e32 v219, 0xffff0000, v45
	v_fmac_f32_e32 v222, v216, v216
	v_fmac_f32_e32 v223, v217, v217
	v_fmac_f32_e32 v222, v218, v218
	v_fmac_f32_e32 v223, v219, v219
	v_lshlrev_b32_e32 v216, 16, v46
	v_and_b32_e32 v217, 0xffff0000, v46
	v_lshlrev_b32_e32 v218, 16, v47
	v_and_b32_e32 v219, 0xffff0000, v47
	v_fmac_f32_e32 v222, v216, v216
	v_fmac_f32_e32 v223, v217, v217
	v_fmac_f32_e32 v222, v218, v218
	v_fmac_f32_e32 v223, v219, v219
	v_add_f32_e32 v222, v222, v223
	s_nop 1
	v_add_f32_dpp v224, v222, v222 quad_perm:[1,0,3,2] row_mask:0xf bank_mask:0xf
	s_nop 1
	v_add_f32_dpp v224, v224, v224 quad_perm:[2,3,0,1] row_mask:0xf bank_mask:0xf
	s_nop 1
	v_add_f32_dpp v224, v224, v224 row_half_mirror row_mask:0xf bank_mask:0xf
	s_nop 1
	v_add_f32_dpp v224, v224, v224 row_mirror row_mask:0xf bank_mask:0xf
	s_nop 1
	v_readlane_b32 s40, v224, 0
	v_readlane_b32 s41, v224, 16
	v_readlane_b32 s42, v224, 32
	v_readlane_b32 s43, v224, 48
	s_nop 1
	v_mov_b32_e32 v225, s40
	v_add_f32_e32 v225, s41, v225
	v_add_f32_e32 v225, s42, v225
	v_add_f32_e32 v225, s43, v225
	v_fmamk_f32 v225, v225, 0x3a000000, v195
	v_rsq_f32_e32 v225, v225
	s_nop 0
	v_lshlrev_b32_e32 v216, 16, v32
	v_and_b32_e32 v217, 0xffff0000, v32
	v_lshlrev_b32_e32 v218, 16, v33
	v_and_b32_e32 v219, 0xffff0000, v33
	v_mul_f32_e32 v216, v225, v216
	v_mul_f32_e32 v217, v225, v217
	v_mul_f32_e32 v218, v225, v218
	v_mul_f32_e32 v219, v225, v219
	v_fmac_f32_e32 v0, v96, v216
	v_fmac_f32_e32 v1, v97, v217
	v_fmac_f32_e32 v2, v98, v218
	v_fmac_f32_e32 v3, v99, v219
	v_lshlrev_b32_e32 v216, 16, v34
	v_and_b32_e32 v217, 0xffff0000, v34
	v_lshlrev_b32_e32 v218, 16, v35
	v_and_b32_e32 v219, 0xffff0000, v35
	v_mul_f32_e32 v216, v225, v216
	v_mul_f32_e32 v217, v225, v217
	v_mul_f32_e32 v218, v225, v218
	v_mul_f32_e32 v219, v225, v219
	v_fmac_f32_e32 v4, v100, v216
	v_fmac_f32_e32 v5, v101, v217
	v_fmac_f32_e32 v6, v102, v218
	v_fmac_f32_e32 v7, v103, v219
	v_lshlrev_b32_e32 v216, 16, v36
	v_and_b32_e32 v217, 0xffff0000, v36
	v_lshlrev_b32_e32 v218, 16, v37
	v_and_b32_e32 v219, 0xffff0000, v37
	v_mul_f32_e32 v216, v225, v216
	v_mul_f32_e32 v217, v225, v217
	v_mul_f32_e32 v218, v225, v218
	v_mul_f32_e32 v219, v225, v219
	v_fmac_f32_e32 v8, v104, v216
	v_fmac_f32_e32 v9, v105, v217
	v_fmac_f32_e32 v10, v106, v218
	v_fmac_f32_e32 v11, v107, v219
	v_lshlrev_b32_e32 v216, 16, v38
	v_and_b32_e32 v217, 0xffff0000, v38
	v_lshlrev_b32_e32 v218, 16, v39
	v_and_b32_e32 v219, 0xffff0000, v39
	v_mul_f32_e32 v216, v225, v216
	v_mul_f32_e32 v217, v225, v217
	v_mul_f32_e32 v218, v225, v218
	v_mul_f32_e32 v219, v225, v219
	v_fmac_f32_e32 v12, v108, v216
	v_fmac_f32_e32 v13, v109, v217
	v_fmac_f32_e32 v14, v110, v218
	v_fmac_f32_e32 v15, v111, v219
	v_lshlrev_b32_e32 v216, 16, v40
	v_and_b32_e32 v217, 0xffff0000, v40
	v_lshlrev_b32_e32 v218, 16, v41
	v_and_b32_e32 v219, 0xffff0000, v41
	v_mul_f32_e32 v216, v225, v216
	v_mul_f32_e32 v217, v225, v217
	v_mul_f32_e32 v218, v225, v218
	v_mul_f32_e32 v219, v225, v219
	v_fmac_f32_e32 v16, v112, v216
	v_fmac_f32_e32 v17, v113, v217
	v_fmac_f32_e32 v18, v114, v218
	v_fmac_f32_e32 v19, v115, v219
	v_lshlrev_b32_e32 v216, 16, v42
	v_and_b32_e32 v217, 0xffff0000, v42
	v_lshlrev_b32_e32 v218, 16, v43
	v_and_b32_e32 v219, 0xffff0000, v43
	v_mul_f32_e32 v216, v225, v216
	v_mul_f32_e32 v217, v225, v217
	v_mul_f32_e32 v218, v225, v218
	v_mul_f32_e32 v219, v225, v219
	v_fmac_f32_e32 v20, v116, v216
	v_fmac_f32_e32 v21, v117, v217
	v_fmac_f32_e32 v22, v118, v218
	v_fmac_f32_e32 v23, v119, v219
	v_lshlrev_b32_e32 v216, 16, v44
	v_and_b32_e32 v217, 0xffff0000, v44
	v_lshlrev_b32_e32 v218, 16, v45
	v_and_b32_e32 v219, 0xffff0000, v45
	v_mul_f32_e32 v216, v225, v216
	v_mul_f32_e32 v217, v225, v217
	v_mul_f32_e32 v218, v225, v218
	v_mul_f32_e32 v219, v225, v219
	v_fmac_f32_e32 v24, v120, v216
	v_fmac_f32_e32 v25, v121, v217
	v_fmac_f32_e32 v26, v122, v218
	v_fmac_f32_e32 v27, v123, v219
; __device__ __forceinline__ unsigned cvt_pk_bf16(float lo, float hi) { unsigned r; asm volatile("v_cvt_pk_bf16_f32 %0, %1, %2" : "=v"(r) : "v"(lo), "v"(hi)); return r; }
; __device__ __forceinline__ float bf_lo(unsigned w) { return __uint_as_float(w << 16); }
; __device__ __forceinline__ float bf_hi(unsigned w) { return __uint_as_float(w & 0xffff0000u); }
; __device__ __forceinline__ float sumsq8(const f32x4 (&v)[8]) {
;     float s = 0.f;
; #pragma unroll
;     for (int j = 0; j < 8; ++j) s += (v[j][0] * v[j][0] + v[j][1] * v[j][1]) + (v[j][2] * v[j][2] + v[j][3] * v[j][3]);
;     return wave_sum(s);
; }
; __device__ __forceinline__ void modulate_store(const f32x4 (&v)[8], float rstd, const float* pn, const float* modr, bf16_t* orow, int lane) {
; #pragma unroll
;     for (int j = 0; j < 8; ++j) { const int col = 4 * lane + 256 * j;
;         const f32x4 g = *(const f32x4*)(pn + col), sh = *(const f32x4*)(modr + col), sc = *(const f32x4*)(modr + DM + col);
;         const f32x4 hh = v[j] * rstd * g * (sc + 1.f) + sh;
;         u32x2 w; w.x = cvt_pk_bf16(hh[0], hh[1]); w.y = cvt_pk_bf16(hh[2], hh[3]);
;         *(u32x2*)(orow + col) = w; }
; }
; __global__ void __launch_bounds__(NWAVES * 64, 2) mk_fwd(Args args) {
;     ...
;                 for (int j = 0; j < 8; ++j) { const int col = 4 * F.lane + 256 * j; const f32x4 gt = *(const f32x4*)(m0 + 2 * DM + col), pn = *(const f32x4*)(post_norm + col);
;                     const f32x4 y4 = (f32x4){bf_lo(yw[q][j].x), bf_hi(yw[q][j].x), bf_lo(yw[q][j].y), bf_hi(yw[q][j].y)};
;                     v[q][j] = v[q][j] + gt * (y4 * rsy * pn);
;                     if (lat) *(f32x4*)(args.out + (size_t)row * DM + col) = v[q][j]; }
;                 const float rstd = __builtin_amdgcn_rsqf(sumsq8(v[q]) * (1.f / DM) + EPS);
;                 modulate_store(v[q], rstd, pre_norm + DM, mod + (size_t)(9 + r) * 6144, H + (size_t)row * DM, F.lane); }
;         }
;     }
	v_lshlrev_b32_e32 v216, 16, v46
	v_and_b32_e32 v217, 0xffff0000, v46
	v_lshlrev_b32_e32 v218, 16, v47
	v_and_b32_e32 v219, 0xffff0000, v47
	v_mul_f32_e32 v216, v225, v216
	v_mul_f32_e32 v217, v225, v217
	v_mul_f32_e32 v218, v225, v218
	v_mul_f32_e32 v219, v225, v219
	v_fmac_f32_e32 v28, v124, v216
	v_fmac_f32_e32 v29, v125, v217
	v_fmac_f32_e32 v30, v126, v218
	v_fmac_f32_e32 v31, v127, v219
	v_mul_f32_e32 v222, v0, v0
	v_mul_f32_e32 v223, v1, v1
	v_fmac_f32_e32 v222, v2, v2
	v_fmac_f32_e32 v223, v3, v3
	v_fmac_f32_e32 v222, v4, v4
	v_fmac_f32_e32 v223, v5, v5
	v_fmac_f32_e32 v222, v6, v6
	v_fmac_f32_e32 v223, v7, v7
	v_fmac_f32_e32 v222, v8, v8
	v_fmac_f32_e32 v223, v9, v9
	v_fmac_f32_e32 v222, v10, v10
	v_fmac_f32_e32 v223, v11, v11
	v_fmac_f32_e32 v222, v12, v12
	v_fmac_f32_e32 v223, v13, v13
	v_fmac_f32_e32 v222, v14, v14
	v_fmac_f32_e32 v223, v15, v15
	v_fmac_f32_e32 v222, v16, v16
	v_fmac_f32_e32 v223, v17, v17
	v_fmac_f32_e32 v222, v18, v18
	v_fmac_f32_e32 v223, v19, v19
	v_fmac_f32_e32 v222, v20, v20
	v_fmac_f32_e32 v223, v21, v21
	v_fmac_f32_e32 v222, v22, v22
	v_fmac_f32_e32 v223, v23, v23
	v_fmac_f32_e32 v222, v24, v24
	v_fmac_f32_e32 v223, v25, v25
	v_fmac_f32_e32 v222, v26, v26
	v_fmac_f32_e32 v223, v27, v27
	v_fmac_f32_e32 v222, v28, v28
	v_fmac_f32_e32 v223, v29, v29
	v_fmac_f32_e32 v222, v30, v30
	v_fmac_f32_e32 v223, v31, v31
	v_add_f32_e32 v222, v222, v223
	s_nop 1
	v_add_f32_dpp v224, v222, v222 quad_perm:[1,0,3,2] row_mask:0xf bank_mask:0xf
	s_nop 1
	v_add_f32_dpp v224, v224, v224 quad_perm:[2,3,0,1] row_mask:0xf bank_mask:0xf
	s_nop 1
	v_add_f32_dpp v224, v224, v224 row_half_mirror row_mask:0xf bank_mask:0xf
	s_nop 1
	v_add_f32_dpp v224, v224, v224 row_mirror row_mask:0xf bank_mask:0xf
	s_nop 1
	v_readlane_b32 s40, v224, 0
	v_readlane_b32 s41, v224, 16
	v_readlane_b32 s42, v224, 32
	v_readlane_b32 s43, v224, 48
	s_nop 1
	v_mov_b32_e32 v225, s40
	v_add_f32_e32 v225, s41, v225
	v_add_f32_e32 v225, s42, v225
	v_add_f32_e32 v225, s43, v225
	v_fmamk_f32 v225, v225, 0x3a000000, v195
	v_rsq_f32_e32 v225, v225
	s_nop 0
	s_add_i32 s0, s6, 0
	s_lshl_b32 s1, s0, 12
	s_add_u32 s26, s84, s1
	s_addc_u32 s27, s85, 0
	s_add_u32 s26, s26, 0x4000000
	s_addc_u32 s27, s27, 0
	v_mul_f32_e32 v216, v225, v0
	v_mul_f32_e32 v217, v225, v1
	v_mul_f32_e32 v218, v225, v2
	v_mul_f32_e32 v219, v225, v3
	v_fma_f32 v216, v216, v128, v160
	v_fma_f32 v217, v217, v129, v161
	v_fma_f32 v218, v218, v130, v162
	v_fma_f32 v219, v219, v131, v163
	v_cvt_pk_bf16_f32 v196, v216, v217
	v_cvt_pk_bf16_f32 v197, v218, v219
	global_store_dwordx2 v194, v[196:197], s[26:27] offset:0
	v_mul_f32_e32 v216, v225, v4
	v_mul_f32_e32 v217, v225, v5
	v_mul_f32_e32 v218, v225, v6
	v_mul_f32_e32 v219, v225, v7
	v_fma_f32 v216, v216, v132, v164
	v_fma_f32 v217, v217, v133, v165
	v_fma_f32 v218, v218, v134, v166
	v_fma_f32 v219, v219, v135, v167
	v_cvt_pk_bf16_f32 v220, v216, v217
	v_cvt_pk_bf16_f32 v221, v218, v219
	global_store_dwordx2 v194, v[220:221], s[26:27] offset:512
	v_mul_f32_e32 v216, v225, v8
	v_mul_f32_e32 v217, v225, v9
	v_mul_f32_e32 v218, v225, v10
	v_mul_f32_e32 v219, v225, v11
	v_fma_f32 v216, v216, v136, v168
	v_fma_f32 v217, v217, v137, v169
	v_fma_f32 v218, v218, v138, v170
	v_fma_f32 v219, v219, v139, v171
	v_cvt_pk_bf16_f32 v196, v216, v217
	v_cvt_pk_bf16_f32 v197, v218, v219
	global_store_dwordx2 v194, v[196:197], s[26:27] offset:1024
	v_mul_f32_e32 v216, v225, v12
	v_mul_f32_e32 v217, v225, v13
	v_mul_f32_e32 v218, v225, v14
	v_mul_f32_e32 v219, v225, v15
	v_fma_f32 v216, v216, v140, v172
	v_fma_f32 v217, v217, v141, v173
	v_fma_f32 v218, v218, v142, v174
	v_fma_f32 v219, v219, v143, v175
	v_cvt_pk_bf16_f32 v220, v216, v217
	v_cvt_pk_bf16_f32 v221, v218, v219
	global_store_dwordx2 v194, v[220:221], s[26:27] offset:1536
	v_mul_f32_e32 v216, v225, v16
	v_mul_f32_e32 v217, v225, v17
	v_mul_f32_e32 v218, v225, v18
	v_mul_f32_e32 v219, v225, v19
	v_fma_f32 v216, v216, v144, v176
	v_fma_f32 v217, v217, v145, v177
	v_fma_f32 v218, v218, v146, v178
	v_fma_f32 v219, v219, v147, v179
	v_cvt_pk_bf16_f32 v196, v216, v217
	v_cvt_pk_bf16_f32 v197, v218, v219
	global_store_dwordx2 v194, v[196:197], s[26:27] offset:2048
	v_mul_f32_e32 v216, v225, v20
	v_mul_f32_e32 v217, v225, v21
	v_mul_f32_e32 v218, v225, v22
	v_mul_f32_e32 v219, v225, v23
	v_fma_f32 v216, v216, v148, v180
	v_fma_f32 v217, v217, v149, v181
	v_fma_f32 v218, v218, v150, v182
	v_fma_f32 v219, v219, v151, v183
	v_cvt_pk_bf16_f32 v220, v216, v217
	v_cvt_pk_bf16_f32 v221, v218, v219
	global_store_dwordx2 v194, v[220:221], s[26:27] offset:2560
	v_mul_f32_e32 v216, v225, v24
	v_mul_f32_e32 v217, v225, v25
	v_mul_f32_e32 v218, v225, v26
	v_mul_f32_e32 v219, v225, v27
	v_fma_f32 v216, v216, v152, v184
	v_fma_f32 v217, v217, v153, v185
	v_fma_f32 v218, v218, v154, v186
	v_fma_f32 v219, v219, v155, v187
	v_cvt_pk_bf16_f32 v196, v216, v217
	v_cvt_pk_bf16_f32 v197, v218, v219
	global_store_dwordx2 v194, v[196:197], s[26:27] offset:3072
	v_mul_f32_e32 v216, v225, v28
	v_mul_f32_e32 v217, v225, v29
	v_mul_f32_e32 v218, v225, v30
	v_mul_f32_e32 v219, v225, v31
	v_fma_f32 v216, v216, v156, v188
	v_fma_f32 v217, v217, v157, v189
	v_fma_f32 v218, v218, v158, v190
	v_fma_f32 v219, v219, v159, v191
	v_cvt_pk_bf16_f32 v220, v216, v217
	v_cvt_pk_bf16_f32 v221, v218, v219
	global_store_dwordx2 v194, v[220:221], s[26:27] offset:3584
	s_add_i32 s0, s6, 2
	s_cmp_lt_u32 s0, 0x4000
	s_cselect_b32 s10, s68, s72
	s_cselect_b32 s11, s69, s73
	s_cselect_b32 s1, 0, 0x4000
	s_sub_i32 s1, s0, s1
	s_lshl_b32 s1, s1, 13
	s_add_u32 s10, s10, s1
	s_addc_u32 s11, s11, 0
	s_add_i32 s0, s6, 2
	s_lshl_b32 s1, s0, 12
	s_add_u32 s22, s84, s1
	s_addc_u32 s23, s85, 0
	s_add_u32 s22, s22, 0x11800000
	s_addc_u32 s23, s23, 0
	global_load_dwordx4 v[0:3], v192, s[10:11] offset:0 nt
	global_load_dwordx4 v[4:7], v192, s[10:11] offset:1024 nt
	global_load_dwordx4 v[8:11], v192, s[10:11] offset:2048 nt
	global_load_dwordx4 v[12:15], v192, s[10:11] offset:3072 nt
	global_load_dwordx4 v[16:19], v193, s[10:11] offset:0 nt
	global_load_dwordx4 v[20:23], v193, s[10:11] offset:1024 nt
	global_load_dwordx4 v[24:27], v193, s[10:11] offset:2048 nt
	global_load_dwordx4 v[28:31], v193, s[10:11] offset:3072 nt
	global_load_dwordx2 v[32:33], v194, s[22:23] offset:0
	global_load_dwordx2 v[34:35], v194, s[22:23] offset:512
	global_load_dwordx2 v[36:37], v194, s[22:23] offset:1024
	global_load_dwordx2 v[38:39], v194, s[22:23] offset:1536
	global_load_dwordx2 v[40:41], v194, s[22:23] offset:2048
	global_load_dwordx2 v[42:43], v194, s[22:23] offset:2560
	global_load_dwordx2 v[44:45], v194, s[22:23] offset:3072
	global_load_dwordx2 v[46:47], v194, s[22:23] offset:3584
	s_add_i32 s0, s6, 1
	s_add_i32 s0, s6, 1
	s_lshr_b32 s8, s0, 11
	s_cmp_lt_u32 s0, 0x4000
	s_cselect_b32 s8, s8, 8
	s_cmp_eq_u32 s8, s7
	s_cbranch_scc1 .Lp6_np1
; __device__ __forceinline__ unsigned cvt_pk_bf16(float lo, float hi) { unsigned r; asm volatile("v_cvt_pk_bf16_f32 %0, %1, %2" : "=v"(r) : "v"(lo), "v"(hi)); return r; }
; __device__ __forceinline__ float bf_lo(unsigned w) { return __uint_as_float(w << 16); }
; __device__ __forceinline__ float bf_hi(unsigned w) { return __uint_as_float(w & 0xffff0000u); }
; __device__ __forceinline__ void modulate_store(const f32x4 (&v)[8], float rstd, const float* pn, const float* modr, bf16_t* orow, int lane) {
; #pragma unroll
;     for (int j = 0; j < 8; ++j) { const int col = 4 * lane + 256 * j;
;         const f32x4 g = *(const f32x4*)(pn + col), sh = *(const f32x4*)(modr + col), sc = *(const f32x4*)(modr + DM + col);
;         const f32x4 hh = v[j] * rstd * g * (sc + 1.f) + sh;
;         u32x2 w; w.x = cvt_pk_bf16(hh[0], hh[1]); w.y = cvt_pk_bf16(hh[2], hh[3]);
;         *(u32x2*)(orow + col) = w; }
; __global__ void __launch_bounds__(NWAVES * 64, 2) mk_fwd(Args args) {
;     ...
;                 const float* m0 = mod + (size_t)r * 6144;
; #pragma unroll
;                 for (int j = 0; j < 8; ++j) { const int col = 4 * F.lane + 256 * j; const f32x4 gt = *(const f32x4*)(m0 + 2 * DM + col), pn = *(const f32x4*)(post_norm + col);
;                     const f32x4 y4 = (f32x4){bf_lo(yw[q][j].x), bf_hi(yw[q][j].x), bf_lo(yw[q][j].y), bf_hi(yw[q][j].y)};
;                     v[q][j] = v[q][j] + gt * (y4 * rsy * pn);
;                     if (lat) *(f32x4*)(args.out + (size_t)row * DM + col) = v[q][j]; }
;                 const float rstd = __builtin_amdgcn_rsqf(sumsq8(v[q]) * (1.f / DM) + EPS);
;                 modulate_store(v[q], rstd, pre_norm + DM, mod + (size_t)(9 + r) * 6144, H + (size_t)row * DM, F.lane); }
	s_mov_b32 s7, s8
	s_add_i32 s1, s8, 9
	s_mul_i32 s1, s1, 0x6000
	s_add_u32 s44, s84, s1
	s_addc_u32 s45, s85, 0
	s_add_u32 s44, s44, 0x2000
	s_addc_u32 s45, s45, 0
	s_add_i32 s1, s8, 9
	s_mul_i32 s1, s1, 0x6000
	s_add_u32 s36, s84, s1
	s_addc_u32 s37, s85, 0
	s_add_u32 s38, s80, 0x2000
	s_addc_u32 s39, s81, 0
	s_mul_i32 s1, s8, 0x6000
	s_add_u32 s34, s84, s1
	s_addc_u32 s35, s85, 0
	s_add_u32 s34, s34, 0x4000
	s_addc_u32 s35, s35, 0
	global_load_dwordx4 v[96:99], v192, s[34:35] offset:0
	global_load_dwordx4 v[200:203], v192, s[82:83] offset:0
	global_load_dwordx4 v[100:103], v192, s[34:35] offset:1024
	global_load_dwordx4 v[204:207], v192, s[82:83] offset:1024
	global_load_dwordx4 v[104:107], v192, s[34:35] offset:2048
	global_load_dwordx4 v[208:211], v192, s[82:83] offset:2048
	global_load_dwordx4 v[108:111], v192, s[34:35] offset:3072
	global_load_dwordx4 v[212:215], v192, s[82:83] offset:3072
	s_waitcnt vmcnt(0)
	v_mul_f32_e32 v96, v96, v200
	v_mul_f32_e32 v97, v97, v201
	v_mul_f32_e32 v98, v98, v202
	v_mul_f32_e32 v99, v99, v203
	v_mul_f32_e32 v100, v100, v204
	v_mul_f32_e32 v101, v101, v205
	v_mul_f32_e32 v102, v102, v206
	v_mul_f32_e32 v103, v103, v207
	v_mul_f32_e32 v104, v104, v208
	v_mul_f32_e32 v105, v105, v209
	v_mul_f32_e32 v106, v106, v210
	v_mul_f32_e32 v107, v107, v211
	v_mul_f32_e32 v108, v108, v212
	v_mul_f32_e32 v109, v109, v213
	v_mul_f32_e32 v110, v110, v214
	v_mul_f32_e32 v111, v111, v215
	global_load_dwordx4 v[128:131], v192, s[38:39] offset:0
	global_load_dwordx4 v[200:203], v192, s[44:45] offset:0
	global_load_dwordx4 v[160:163], v192, s[36:37] offset:0
	global_load_dwordx4 v[132:135], v192, s[38:39] offset:1024
	global_load_dwordx4 v[204:207], v192, s[44:45] offset:1024
	global_load_dwordx4 v[164:167], v192, s[36:37] offset:1024
	global_load_dwordx4 v[136:139], v192, s[38:39] offset:2048
	global_load_dwordx4 v[208:211], v192, s[44:45] offset:2048
	global_load_dwordx4 v[168:171], v192, s[36:37] offset:2048
	global_load_dwordx4 v[140:143], v192, s[38:39] offset:3072
	global_load_dwordx4 v[212:215], v192, s[44:45] offset:3072
	global_load_dwordx4 v[172:175], v192, s[36:37] offset:3072
	s_waitcnt vmcnt(0)
	v_add_f32_e32 v200, 1.0, v200
	v_add_f32_e32 v201, 1.0, v201
	v_add_f32_e32 v202, 1.0, v202
	v_add_f32_e32 v203, 1.0, v203
	v_mul_f32_e32 v128, v128, v200
	v_mul_f32_e32 v129, v129, v201
	v_mul_f32_e32 v130, v130, v202
	v_mul_f32_e32 v131, v131, v203
	v_add_f32_e32 v204, 1.0, v204
	v_add_f32_e32 v205, 1.0, v205
	v_add_f32_e32 v206, 1.0, v206
	v_add_f32_e32 v207, 1.0, v207
	v_mul_f32_e32 v132, v132, v204
	v_mul_f32_e32 v133, v133, v205
	v_mul_f32_e32 v134, v134, v206
	v_mul_f32_e32 v135, v135, v207
	v_add_f32_e32 v208, 1.0, v208
	v_add_f32_e32 v209, 1.0, v209
	v_add_f32_e32 v210, 1.0, v210
	v_add_f32_e32 v211, 1.0, v211
	v_mul_f32_e32 v136, v136, v208
	v_mul_f32_e32 v137, v137, v209
	v_mul_f32_e32 v138, v138, v210
	v_mul_f32_e32 v139, v139, v211
	v_add_f32_e32 v212, 1.0, v212
	v_add_f32_e32 v213, 1.0, v213
	v_add_f32_e32 v214, 1.0, v214
	v_add_f32_e32 v215, 1.0, v215
	v_mul_f32_e32 v140, v140, v212
	v_mul_f32_e32 v141, v141, v213
	v_mul_f32_e32 v142, v142, v214
	v_mul_f32_e32 v143, v143, v215
	global_load_dwordx4 v[112:115], v193, s[34:35] offset:0
	global_load_dwordx4 v[200:203], v193, s[82:83] offset:0
	global_load_dwordx4 v[116:119], v193, s[34:35] offset:1024
	global_load_dwordx4 v[204:207], v193, s[82:83] offset:1024
	global_load_dwordx4 v[120:123], v193, s[34:35] offset:2048
	global_load_dwordx4 v[208:211], v193, s[82:83] offset:2048
	global_load_dwordx4 v[124:127], v193, s[34:35] offset:3072
	global_load_dwordx4 v[212:215], v193, s[82:83] offset:3072
	s_waitcnt vmcnt(0)
	v_mul_f32_e32 v112, v112, v200
	v_mul_f32_e32 v113, v113, v201
	v_mul_f32_e32 v114, v114, v202
	v_mul_f32_e32 v115, v115, v203
	v_mul_f32_e32 v116, v116, v204
	v_mul_f32_e32 v117, v117, v205
	v_mul_f32_e32 v118, v118, v206
	v_mul_f32_e32 v119, v119, v207
	v_mul_f32_e32 v120, v120, v208
	v_mul_f32_e32 v121, v121, v209
	v_mul_f32_e32 v122, v122, v210
	v_mul_f32_e32 v123, v123, v211
	v_mul_f32_e32 v124, v124, v212
	v_mul_f32_e32 v125, v125, v213
	v_mul_f32_e32 v126, v126, v214
	v_mul_f32_e32 v127, v127, v215
	global_load_dwordx4 v[144:147], v193, s[38:39] offset:0
	global_load_dwordx4 v[200:203], v193, s[44:45] offset:0
	global_load_dwordx4 v[176:179], v193, s[36:37] offset:0
	global_load_dwordx4 v[148:151], v193, s[38:39] offset:1024
	global_load_dwordx4 v[204:207], v193, s[44:45] offset:1024
	global_load_dwordx4 v[180:183], v193, s[36:37] offset:1024
	global_load_dwordx4 v[152:155], v193, s[38:39] offset:2048
	global_load_dwordx4 v[208:211], v193, s[44:45] offset:2048
	global_load_dwordx4 v[184:187], v193, s[36:37] offset:2048
	global_load_dwordx4 v[156:159], v193, s[38:39] offset:3072
	global_load_dwordx4 v[212:215], v193, s[44:45] offset:3072
	global_load_dwordx4 v[188:191], v193, s[36:37] offset:3072
	s_waitcnt vmcnt(0)
	v_add_f32_e32 v200, 1.0, v200
	v_add_f32_e32 v201, 1.0, v201
	v_add_f32_e32 v202, 1.0, v202
	v_add_f32_e32 v203, 1.0, v203
	v_mul_f32_e32 v144, v144, v200
	v_mul_f32_e32 v145, v145, v201
	v_mul_f32_e32 v146, v146, v202
	v_mul_f32_e32 v147, v147, v203
	v_add_f32_e32 v204, 1.0, v204
	v_add_f32_e32 v205, 1.0, v205
	v_add_f32_e32 v206, 1.0, v206
	v_add_f32_e32 v207, 1.0, v207
	v_mul_f32_e32 v148, v148, v204
	v_mul_f32_e32 v149, v149, v205
	v_mul_f32_e32 v150, v150, v206
	v_mul_f32_e32 v151, v151, v207
	v_add_f32_e32 v208, 1.0, v208
	v_add_f32_e32 v209, 1.0, v209
	v_add_f32_e32 v210, 1.0, v210
	v_add_f32_e32 v211, 1.0, v211
	v_mul_f32_e32 v152, v152, v208
	v_mul_f32_e32 v153, v153, v209
	v_mul_f32_e32 v154, v154, v210
	v_mul_f32_e32 v155, v155, v211
	v_add_f32_e32 v212, 1.0, v212
	v_add_f32_e32 v213, 1.0, v213
	v_add_f32_e32 v214, 1.0, v214
	v_add_f32_e32 v215, 1.0, v215
	v_mul_f32_e32 v156, v156, v212
	v_mul_f32_e32 v157, v157, v213
	v_mul_f32_e32 v158, v158, v214
	v_mul_f32_e32 v159, v159, v215
